# PGATE+PLE phases: half of each XCD's workgroups run PGATE(u0) PLE(u0) PGATE(u1) PLE(u1) so memory-bound PLE epilogues overlap the other half's MFMA-bound PGATE main loops
# speedup vs baseline: 1.0040x; 1.0019x over previous
.LBB0_5:
	s_or_b64 exec, exec, s[2:3]
	s_mov_b32 s7, 0
	v_writelane_b32 v255, s7, 41
	s_cmp_ge_i32 s74, s75
	s_cbranch_scc0 .LBB0_6
	s_getpc_b64 s[98:99]

.Lple_reenter:
	s_lshr_b32 s4, 0x21040200, s74
	s_lshr_b32 s5, s34, 3
	s_and_b32 s4, s4, s5
	s_and_b32 s4, s4, 1
	s_cmp_eq_u32 s4, 0
	s_cbranch_scc1 .Lple_cont
	v_readlane_b32 s4, v255, 41
	s_cmp_lg_u32 s4, 0
	s_cbranch_scc1 .Lple_cont
	v_writelane_b32 v255, s22, 42
	v_writelane_b32 v255, s36, 43
	v_writelane_b32 v255, s37, 44
	v_writelane_b32 v255, s10, 45
	v_writelane_b32 v255, s11, 46
	s_mov_b32 s22, 0x100000
.Lple_cont:
	v_writelane_b32 v254, s72, 50
	s_lshl_b32 s89, s23, 7
	s_lshl_b32 s92, s86, 7
	v_writelane_b32 v254, s73, 51
	v_writelane_b32 v254, s74, 52
	v_writelane_b32 v254, s75, 53
	s_waitcnt vmcnt(0)
	v_bfe_i32 v4, v166, 27, 1
	v_readlane_b32 s4, v254, 6
	v_readlane_b32 s5, v254, 7
	s_xor_b64 s[46:47], s[4:5], -1
	s_cmp_ge_i32 s34, s89
	s_cselect_b64 s[4:5], -1, 0
	s_sub_i32 s6, s34, s89
	s_sub_i32 s20, s6, s92
	v_lshlrev_b32_e32 v2, 4, v166
	v_lshrrev_b32_e32 v4, 22, v4
	s_cmp_lt_i32 s6, s92
	v_add_u32_e32 v4, v2, v4
	s_cselect_b64 s[18:19], -1, 0
	v_and_b32_e32 v4, 0xfffffc00, v4
	s_and_b64 s[8:9], s[18:19], exec
	v_sub_u32_e32 v4, v2, v4
	s_cselect_b32 s6, s6, s20
	s_and_b64 s[4:5], s[4:5], s[18:19]
	v_lshrrev_b32_e32 v5, 4, v4
	s_and_b64 s[8:9], s[4:5], exec
	v_lshrrev_b32_e32 v3, 26, v167
	v_bitop3_b32 v4, v5, v4, 32 bitop3:0x6c
	s_cselect_b32 s21, s88, s65
	s_cmp_lt_i32 s34, s89
	v_add_u32_e32 v3, v166, v3
	v_ashrrev_i32_e32 v6, 31, v4
	s_cselect_b64 s[8:9], -1, 0
	v_ashrrev_i32_e32 v3, 6, v3
	v_lshrrev_b32_e32 v6, 26, v6
	s_and_b64 s[8:9], s[8:9], exec
	v_lshlrev_b32_e32 v5, 3, v3
	v_add_u32_e32 v6, v4, v6
	s_cselect_b32 s21, 0, s21
	s_and_b64 s[8:9], s[4:5], exec
	v_and_b32_e32 v5, -16, v5
	v_ashrrev_i32_e32 v7, 6, v6
	s_cselect_b32 s24, s87, s64
	s_cmp_lt_i32 s34, s89
	s_waitcnt vmcnt(7)
	v_add_u32_e32 v200, v7, v5
	v_and_b32_e32 v5, 0xc0, v6
	s_cselect_b64 s[8:9], -1, 0
	v_lshlrev_b32_e32 v3, 5, v3
	v_sub_u32_e32 v4, v4, v5
	s_and_b64 s[8:9], s[8:9], exec
	v_and_b32_e32 v3, 32, v3
	v_ashrrev_i16_sdwa v4, v223, sext(v4) dst_sel:DWORD dst_unused:UNUSED_PAD src0_sel:DWORD src1_sel:BYTE_0
	v_add_u32_sdwa v201, v3, sext(v4) dst_sel:DWORD dst_unused:UNUSED_PAD src0_sel:DWORD src1_sel:WORD_0
	v_lshlrev_b32_e32 v3, 1, v200
	v_lshrrev_b32_e32 v4, 2, v200
	v_and_b32_e32 v5, 3, v7
	s_mov_b32 s8, 0x7fffffe0
	v_and_b32_e32 v3, 24, v3
	v_and_b32_e32 v4, 4, v4
	v_and_or_b32 v5, v200, s8, v5
	v_add_u32_e32 v2, 0x2000, v2
	s_waitcnt vmcnt(6)
	v_or3_b32 v202, v5, v4, v3
	v_ashrrev_i32_e32 v3, 31, v2
	v_lshrrev_b32_e32 v3, 22, v3
	v_add_u32_e32 v3, v2, v3
	v_ashrrev_i32_e32 v3, 10, v3
	v_mul_i32_i24_e32 v4, 0x400, v3
	v_sub_u32_e32 v2, v2, v4
	v_lshrrev_b32_e32 v4, 4, v2
	v_bitop3_b32 v2, v4, v2, 32 bitop3:0x6c
	v_ashrrev_i32_e32 v5, 31, v2
	v_lshrrev_b32_e32 v5, 26, v5
	v_lshlrev_b32_e32 v4, 3, v3
	v_add_u32_e32 v5, v2, v5
	s_cselect_b32 s24, 0, s24
	s_and_b64 s[4:5], s[4:5], exec
	v_and_b32_e32 v4, -16, v4
	v_ashrrev_i32_e32 v6, 6, v5
	s_cselect_b32 s25, s86, s35
	s_cmp_lt_i32 s34, s89
	v_add_u32_e32 v203, v6, v4
	v_and_b32_e32 v4, 0xc0, v5
	s_cselect_b64 s[4:5], -1, 0
	v_sub_u32_e32 v2, v2, v4
	v_and_b32_e32 v4, 3, v6
	v_and_or_b32 v4, v203, s8, v4
	s_and_b64 s[8:9], s[4:5], exec
	s_cselect_b32 s6, s34, s6
	s_cselect_b32 s25, s23, s25
	s_lshl_b32 s8, s35, 7
	v_readlane_b32 s30, v254, 8
	s_cmp_lt_i32 s20, s8
	v_readlane_b32 s31, v254, 9
	v_writelane_b32 v253, s8, 53
	s_cselect_b64 s[8:9], -1, 0
	s_xor_b64 s[30:31], s[30:31], -1
	v_writelane_b32 v254, s30, 54
	s_and_b64 s[8:9], s[30:31], s[8:9]
	v_lshlrev_b32_e32 v3, 5, v3
	s_or_b64 s[8:9], s[18:19], s[8:9]
	v_and_b32_e32 v3, 32, v3
	v_ashrrev_i16_sdwa v2, v223, sext(v2) dst_sel:DWORD dst_unused:UNUSED_PAD src0_sel:DWORD src1_sel:BYTE_0
	s_and_b64 s[8:9], s[46:47], s[8:9]
	s_waitcnt vmcnt(5)
	v_add_u32_sdwa v204, v3, sext(v2) dst_sel:DWORD dst_unused:UNUSED_PAD src0_sel:DWORD src1_sel:WORD_0
	v_lshlrev_b32_e32 v2, 1, v203
	v_lshrrev_b32_e32 v3, 2, v203
	v_writelane_b32 v254, s31, 55
	s_or_b64 s[30:31], s[4:5], s[8:9]
	s_lshl_b32 s9, s25, 3
	v_and_b32_e32 v2, 24, v2
	v_and_b32_e32 v3, 4, v3
	s_abs_i32 s18, s9
	v_or3_b32 v205, v4, v3, v2
	v_cvt_f32_u32_e32 v4, s18
	s_ashr_i32 s5, s6, 31
	s_lshr_b32 s5, s5, 29
	s_add_i32 s5, s6, s5
	v_rcp_iflag_f32_e32 v4, v4
	s_ashr_i32 s8, s5, 3
	s_and_b32 s5, s5, -8
	s_sub_i32 s5, s6, s5
	v_mul_f32_e32 v4, 0x4f7ffffe, v4
	v_cvt_u32_f32_e32 v4, v4
	s_lshl_b32 s4, s25, 4
	s_lshr_b32 s6, s5, 31
	s_or_b32 s4, s4, s6
	s_mul_i32 s4, s4, s5
	s_add_i32 s4, s4, s8
	s_sub_i32 s8, 0, s18
	v_readfirstlane_b32 s19, v4
	s_mul_i32 s8, s8, s19
	s_mul_hi_u32 s8, s19, s8
	s_abs_i32 s6, s4
	s_add_i32 s19, s19, s8
	s_mul_hi_u32 s8, s6, s19
	s_mul_i32 s19, s8, s18
	s_xor_b32 s5, s4, s9
	s_sub_i32 s6, s6, s19
	s_ashr_i32 s5, s5, 31
	s_add_i32 s19, s8, 1
	s_sub_i32 s20, s6, s18
	s_cmp_ge_u32 s6, s18
	s_cselect_b32 s8, s19, s8
	s_cselect_b32 s6, s20, s6
	s_add_i32 s19, s8, 1
	s_cmp_ge_u32 s6, s18
	s_cselect_b32 s6, s19, s8
	s_xor_b32 s6, s6, s5
	s_sub_i32 s5, s6, s5
	s_lshl_b32 s6, s5, 3
	s_sub_i32 s8, 0x80, s6
	s_min_i32 s8, s8, 8
	s_abs_i32 s18, s8
	v_cvt_f32_u32_e32 v4, s18
	v_bfe_u32 v0, v166, 4, 2
	s_waitcnt vmcnt(4)
	v_lshlrev_b32_e32 v207, 3, v0
	s_waitcnt vmcnt(3)
	v_lshlrev_b32_e32 v208, 4, v0
	v_cmp_eq_u32_e64 s[40:41], 0, v0
	v_rcp_iflag_f32_e32 v0, v4
	s_sub_i32 s19, 0, s18
	s_mul_i32 s5, s5, s9
	s_sub_i32 s4, s4, s5
	v_mul_f32_e32 v0, 0x4f7ffffe, v0
	v_cvt_u32_f32_e32 v0, v0
	s_abs_i32 s9, s4
	s_xor_b32 s5, s4, s8
	s_add_i32 s6, s6, s24
	v_readfirstlane_b32 s20, v0
	s_mul_i32 s19, s19, s20
	s_mul_hi_u32 s19, s20, s19
	s_add_i32 s20, s20, s19
	s_mul_hi_u32 s19, s9, s20
	s_mul_i32 s20, s19, s18
	s_sub_i32 s9, s9, s20
	s_ashr_i32 s5, s5, 31
	s_add_i32 s20, s19, 1
	s_sub_i32 s24, s9, s18
	s_cmp_ge_u32 s9, s18
	s_cselect_b32 s19, s20, s19
	s_cselect_b32 s9, s24, s9
	s_add_i32 s20, s19, 1
	s_cmp_ge_u32 s9, s18
	s_cselect_b32 s9, s20, s19
	s_xor_b32 s9, s9, s5
	s_sub_i32 s5, s9, s5
	s_mul_i32 s8, s5, s8
	s_sub_i32 s4, s4, s8
	s_add_i32 s4, s6, s4
	v_writelane_b32 v254, s4, 56
	s_add_i32 s4, s5, s21
	v_and_b32_e32 v206, 15, v166
	v_lshlrev_b32_e32 v3, 2, v166
	v_writelane_b32 v254, s4, 58
	v_lshlrev_b32_e32 v2, 6, v206
	v_and_b32_e32 v3, 32, v3
	v_readlane_b32 s4, v254, 26
	v_writelane_b32 v254, s30, 60
	s_mov_b32 s93, 0
	s_movk_i32 s94, 0x400
	v_bitop3_b32 v209, v208, v3, v2 bitop3:0x36
	v_writelane_b32 v254, s31, 61
	s_branch .LBB0_901

.LBB0_1479:
	v_readlane_b32 s72, v254, 50
	v_readlane_b32 s70, v253, 37
	v_readlane_b32 s76, v253, 39
	v_readlane_b32 s90, v253, 41
	v_readlane_b32 s92, v253, 43
	v_readlane_b32 s73, v254, 51
	v_readlane_b32 s74, v254, 52
	v_readlane_b32 s75, v254, 53
	v_readlane_b32 s71, v253, 38
	v_readlane_b32 s77, v253, 40
	v_readlane_b32 s91, v253, 42
	v_readlane_b32 s93, v253, 44
	s_lshr_b32 s4, 0x21040200, s74
	s_lshr_b32 s5, s34, 3
	s_and_b32 s4, s4, s5
	s_and_b32 s4, s4, 1
	s_cmp_eq_u32 s4, 0
	s_cbranch_scc1 .Lple_end
	v_readlane_b32 s4, v255, 41
	s_cmp_eq_u32 s4, 0
	s_cbranch_scc0 .Lple_second_done
	s_mov_b32 s4, 1
	v_writelane_b32 v255, s4, 41
	s_add_i32 s34, s34, 0x100
	v_readlane_b32 s36, v255, 43
	v_readlane_b32 s37, v255, 44
	v_readlane_b32 s10, v255, 45
	v_readlane_b32 s11, v255, 46
	s_branch .Lple_reenter
.Lple_second_done:
	s_mov_b32 s4, 0
	v_writelane_b32 v255, s4, 41
	s_sub_i32 s34, s34, 0x100
	v_readlane_b32 s22, v255, 42
.Lple_end:
	s_movk_i32 s96, 0x110
